# adds: ssma recurrence with batched LDS reads + plain fma; m2 skip-term loads batched; sgemm residual row loaded at item start; sgemm K=2816 6-slot load ring; m2 carry-in batches
# speedup vs baseline: 1.0121x; 1.0032x over previous
.LBB0_323:
	s_and_b32 s6, s12, 0xffffffe0
	v_or_b32_e32 v6, s6, v21
	v_ashrrev_i32_e32 v7, 31, v6
	v_lshlrev_b64 v[6:7], 11, v[6:7]
	s_and_b32 s15, s14, 15
	v_add_u32_e32 v250, s6, v8
	v_ashrrev_i32_e32 v251, 31, v250
	v_lshlrev_b64 v[250:251], 11, v[250:251]
	v_lshl_add_u64 v[250:251], s[8:9], 0, v[250:251]
	s_lshl_b32 s24, s15, 7
	v_lshl_add_u64 v[250:251], v[250:251], 0, s[24:25]
	v_mov_b32_e32 v252, v4
	v_mov_b32_e32 v253, v20
	v_lshl_add_u64 v[250:251], v[250:251], 0, v[252:253]
	global_load_dwordx2 v[252:253], v[250:251], off
	v_lshl_add_u64 v[6:7], v[0:1], 0, v[6:7]
	v_lshlrev_b32_e32 v5, 11, v21
	v_lshl_or_b32 v16, s15, 17, v5
	v_mov_b32_e32 v17, v20
	v_add_co_u32_e32 v78, vcc, 0x8000, v6
	v_lshl_add_u64 v[86:87], v[2:3], 0, v[16:17]
	s_nop 0
	v_addc_co_u32_e32 v79, vcc, 0, v7, vcc
	v_add_co_u32_e32 v94, vcc, 0x8000, v86
	s_mov_b32 s7, 0x18000
	s_nop 0
	v_addc_co_u32_e32 v95, vcc, 0, v87, vcc
	v_add_co_u32_e32 v102, vcc, s80, v86
	s_nop 1
	v_addc_co_u32_e32 v103, vcc, 0, v87, vcc
	v_add_co_u32_e32 v110, vcc, s7, v86
	s_nop 1
	v_addc_co_u32_e32 v111, vcc, 0, v87, vcc
	global_load_dwordx4 v[16:19], v[6:7], off
	global_load_dwordx4 v[22:25], v[6:7], off offset:64
	global_load_dwordx4 v[26:29], v[78:79], off
	global_load_dwordx4 v[30:33], v[78:79], off offset:64
	global_load_dwordx4 v[34:37], v[86:87], off
	global_load_dwordx4 v[38:41], v[86:87], off offset:64
	global_load_dwordx4 v[42:45], v[94:95], off
	global_load_dwordx4 v[46:49], v[94:95], off offset:64
	global_load_dwordx4 v[50:53], v[102:103], off
	global_load_dwordx4 v[54:57], v[102:103], off offset:64
	global_load_dwordx4 v[58:61], v[110:111], off
	global_load_dwordx4 v[62:65], v[110:111], off offset:64
	global_load_dwordx4 v[66:69], v[6:7], off offset:128
	global_load_dwordx4 v[70:73], v[6:7], off offset:192
	global_load_dwordx4 v[74:77], v[78:79], off offset:128
	s_nop 0
	global_load_dwordx4 v[78:81], v[78:79], off offset:192
	s_nop 0
	global_load_dwordx4 v[82:85], v[86:87], off offset:128
	s_nop 0
	global_load_dwordx4 v[86:89], v[86:87], off offset:192
	s_nop 0
	global_load_dwordx4 v[90:93], v[94:95], off offset:128
	s_nop 0
	global_load_dwordx4 v[94:97], v[94:95], off offset:192
	s_nop 0
	global_load_dwordx4 v[98:101], v[102:103], off offset:128
	s_nop 0
	global_load_dwordx4 v[102:105], v[102:103], off offset:192
	s_nop 0
	global_load_dwordx4 v[106:109], v[110:111], off offset:128
	s_nop 0
	global_load_dwordx4 v[110:113], v[110:111], off offset:192
	s_waitcnt vmcnt(19)
	v_mfma_f32_16x16x32_bf16 v[114:117], v[34:37], v[16:19], 0
	s_waitcnt vmcnt(17)
	v_mfma_f32_16x16x32_bf16 v[118:121], v[42:45], v[16:19], 0
	s_waitcnt vmcnt(15)
	v_mfma_f32_16x16x32_bf16 v[122:125], v[50:53], v[16:19], 0
	s_waitcnt vmcnt(13)
	v_mfma_f32_16x16x32_bf16 v[16:19], v[58:61], v[16:19], 0
	v_mfma_f32_16x16x32_bf16 v[34:37], v[34:37], v[26:29], 0
	v_mfma_f32_16x16x32_bf16 v[42:45], v[42:45], v[26:29], 0
	v_mfma_f32_16x16x32_bf16 v[50:53], v[50:53], v[26:29], 0
	v_mfma_f32_16x16x32_bf16 v[26:29], v[58:61], v[26:29], 0
	v_mfma_f32_16x16x32_bf16 v[58:61], v[38:41], v[22:25], v[114:117]
	v_mfma_f32_16x16x32_bf16 v[114:117], v[46:49], v[22:25], v[118:121]
	v_mfma_f32_16x16x32_bf16 v[118:121], v[54:57], v[22:25], v[122:125]
	s_waitcnt vmcnt(12)
	v_mfma_f32_16x16x32_bf16 v[16:19], v[62:65], v[22:25], v[16:19]
	v_mfma_f32_16x16x32_bf16 v[22:25], v[38:41], v[30:33], v[34:37]
	v_mfma_f32_16x16x32_bf16 v[34:37], v[46:49], v[30:33], v[42:45]
	v_mfma_f32_16x16x32_bf16 v[38:41], v[54:57], v[30:33], v[50:53]
	v_mfma_f32_16x16x32_bf16 v[26:29], v[62:65], v[30:33], v[26:29]
	s_waitcnt vmcnt(7)
	v_mfma_f32_16x16x32_bf16 v[30:33], v[82:85], v[66:69], v[58:61]
	s_waitcnt vmcnt(5)
	v_mfma_f32_16x16x32_bf16 v[42:45], v[90:93], v[66:69], v[114:117]
	s_waitcnt vmcnt(3)
	v_mfma_f32_16x16x32_bf16 v[46:49], v[98:101], v[66:69], v[118:121]
	s_waitcnt vmcnt(1)
	v_mfma_f32_16x16x32_bf16 v[16:19], v[106:109], v[66:69], v[16:19]
	v_mfma_f32_16x16x32_bf16 v[22:25], v[82:85], v[74:77], v[22:25]
	v_mfma_f32_16x16x32_bf16 v[34:37], v[90:93], v[74:77], v[34:37]
	v_mfma_f32_16x16x32_bf16 v[38:41], v[98:101], v[74:77], v[38:41]
	v_mfma_f32_16x16x32_bf16 v[26:29], v[106:109], v[74:77], v[26:29]
	v_mfma_f32_16x16x32_bf16 v[30:33], v[86:89], v[70:73], v[30:33]
	v_mfma_f32_16x16x32_bf16 v[42:45], v[94:97], v[70:73], v[42:45]
	v_mfma_f32_16x16x32_bf16 v[46:49], v[102:105], v[70:73], v[46:49]
	s_waitcnt vmcnt(0)
	v_mfma_f32_16x16x32_bf16 v[16:19], v[110:113], v[70:73], v[16:19]
	v_mfma_f32_16x16x32_bf16 v[22:25], v[86:89], v[78:81], v[22:25]
	v_mfma_f32_16x16x32_bf16 v[34:37], v[94:97], v[78:81], v[34:37]
	v_mfma_f32_16x16x32_bf16 v[38:41], v[102:105], v[78:81], v[38:41]
	v_mfma_f32_16x16x32_bf16 v[26:29], v[110:113], v[78:81], v[26:29]
	ds_write_b128 v14, v[30:33]
	ds_write_b128 v14, v[42:45] offset:64
	ds_write_b128 v14, v[46:49] offset:128
	s_nop 0
	ds_write_b128 v14, v[16:19] offset:192
	ds_write_b128 v14, v[22:25] offset:4096
	ds_write_b128 v14, v[34:37] offset:4160
	ds_write_b128 v14, v[38:41] offset:4224
	ds_write_b128 v14, v[26:29] offset:4288
	s_waitcnt lgkmcnt(0)
	s_barrier
	ds_read_b128 v[16:19], v9
	ds_read_b128 v[22:25], v9 offset:8192
	s_lshl_b32 s24, s15, 7
	v_mov_b32_e32 v5, v20
	s_waitcnt lgkmcnt(0)
	v_pk_add_f32 v[6:7], v[18:19], v[24:25]
	v_pk_add_f32 v[22:23], v[16:17], v[22:23]
	ds_read_b128 v[16:19], v9 offset:16384
	s_waitcnt lgkmcnt(0)
	v_pk_add_f32 v[6:7], v[6:7], v[18:19]
	v_pk_add_f32 v[22:23], v[22:23], v[16:17]
	ds_read_b128 v[16:19], v9 offset:24576
	s_waitcnt lgkmcnt(0)
	v_pk_add_f32 v[6:7], v[6:7], v[18:19]
	v_pk_add_f32 v[22:23], v[22:23], v[16:17]
	ds_read_b128 v[16:19], v9 offset:32768
	s_waitcnt lgkmcnt(0)
	v_pk_add_f32 v[6:7], v[6:7], v[18:19]
	v_pk_add_f32 v[22:23], v[22:23], v[16:17]
	ds_read_b128 v[16:19], v9 offset:40960
	s_waitcnt lgkmcnt(0)
	v_pk_add_f32 v[6:7], v[6:7], v[18:19]
	v_pk_add_f32 v[22:23], v[22:23], v[16:17]
	ds_read_b128 v[16:19], v9 offset:49152
	s_waitcnt lgkmcnt(0)
	v_pk_add_f32 v[6:7], v[6:7], v[18:19]
	v_pk_add_f32 v[22:23], v[22:23], v[16:17]
	ds_read_b128 v[16:19], v9 offset:57344
	s_waitcnt lgkmcnt(0)
	v_pk_add_f32 v[18:19], v[6:7], v[18:19]
	v_add_u32_e32 v6, s6, v8
	v_ashrrev_i32_e32 v7, 31, v6
	v_pk_add_f32 v[16:17], v[22:23], v[16:17]
	v_lshlrev_b64 v[22:23], 11, v[6:7]
	v_lshl_add_u64 v[22:23], s[8:9], 0, v[22:23]
	v_lshl_add_u64 v[22:23], v[22:23], 0, s[24:25]
	v_lshl_add_u64 v[22:23], v[22:23], 0, v[4:5]
	v_mov_b32_e32 v24, v252
	v_mov_b32_e32 v25, v253
	s_waitcnt vmcnt(0)
	v_lshlrev_b32_e32 v26, 16, v24
	v_and_b32_e32 v27, 0xffff0000, v24
	v_lshlrev_b32_e32 v24, 16, v25
	v_and_b32_e32 v25, 0xffff0000, v25
	v_pk_add_f32 v[18:19], v[18:19], v[24:25]
	v_pk_add_f32 v[16:17], v[16:17], v[26:27]
	v_mul_f32_e32 v15, v19, v19
	v_mul_f32_e32 v5, v17, v17
	v_fmac_f32_e32 v5, v16, v16
	v_fmac_f32_e32 v15, v18, v18
	v_add_f32_e32 v5, v5, v15
	ds_bpermute_b32 v15, v10, v5
	v_cvt_pk_bf16_f32 v24, v16, v17
	v_cvt_pk_bf16_f32 v25, v18, v19
	global_store_dwordx2 v[22:23], v[24:25], off
	s_waitcnt lgkmcnt(0)
	v_add_f32_e32 v5, v5, v15
	ds_bpermute_b32 v15, v11, v5
	s_waitcnt lgkmcnt(0)
	v_add_f32_e32 v5, v5, v15
	ds_bpermute_b32 v15, v12, v5
	s_waitcnt lgkmcnt(0)
	v_add_f32_e32 v5, v5, v15
	ds_bpermute_b32 v15, v13, v5
	s_and_saveexec_b64 s[6:7], s[38:39]
	s_cbranch_execz .LBB0_322
	v_lshlrev_b64 v[6:7], 6, v[6:7]
	v_lshl_add_u64 v[6:7], s[10:11], 0, v[6:7]
	s_lshl_b32 s24, s15, 2
	s_waitcnt lgkmcnt(0)
	v_add_f32_e32 v5, v5, v15
	v_lshl_add_u64 v[6:7], v[6:7], 0, s[24:25]
	global_store_dword v[6:7], v5, off
	s_branch .LBB0_322

.LBB0_368:
	s_or_b64 exec, exec, s[12:13]
	v_lshl_add_u64 v[38:39], v[130:131], 1, v[86:87]
	v_lshl_add_u64 v[42:43], v[38:39], 0, v[74:75]
	global_load_ushort v41, v[42:43], off
	v_lshl_add_u64 v[42:43], v[38:39], 0, v[98:99]
	v_lshl_add_u64 v[44:45], v[38:39], 0, v[100:101]
	global_load_ushort v42, v[42:43], off
	v_mov_b32_e32 v179, 0
	global_load_ushort v43, v[44:45], off
	v_lshl_add_u64 v[44:45], v[38:39], 0, v[102:103]
	global_load_ushort v44, v[44:45], off
	s_and_b64 vcc, exec, s[38:39]
	s_cbranch_vccnz .Lm2u_zero
	v_lshl_add_u64 v[46:47], v[38:39], 0, v[104:105]
	global_load_ushort v180, v[46:47], off
	v_lshl_add_u64 v[46:47], v[38:39], 0, v[106:107]
	global_load_ushort v179, v[46:47], off
	v_lshl_add_u64 v[46:47], v[38:39], 0, v[108:109]
	global_load_ushort v178, v[46:47], off
	v_lshl_add_u64 v[46:47], v[38:39], 0, v[110:111]
	global_load_ushort v177, v[46:47], off
	v_lshl_add_u64 v[46:47], v[38:39], 0, v[112:113]
	global_load_ushort v162, v[46:47], off
	v_lshl_add_u64 v[46:47], v[38:39], 0, v[114:115]
	global_load_ushort v148, v[46:47], off
	v_lshl_add_u64 v[46:47], v[38:39], 0, v[116:117]
	global_load_ushort v147, v[46:47], off
	v_lshl_add_u64 v[46:47], v[38:39], 0, v[118:119]
	global_load_ushort v146, v[46:47], off
	v_lshl_add_u64 v[46:47], v[38:39], 0, v[120:121]
	global_load_ushort v144, v[46:47], off
	v_lshl_add_u64 v[46:47], v[38:39], 0, v[122:123]
	global_load_ushort v142, v[46:47], off
	v_lshl_add_u64 v[46:47], v[38:39], 0, v[124:125]
	global_load_ushort v143, v[46:47], off
	v_lshl_add_u64 v[46:47], v[38:39], 0, v[126:127]
	global_load_ushort v131, v[46:47], off
	s_waitcnt vmcnt(0)
	v_lshlrev_b32_e32 v180, 16, v180
	v_lshlrev_b32_e32 v179, 16, v179
	v_lshlrev_b32_e32 v178, 16, v178
	v_lshlrev_b32_e32 v177, 16, v177
	v_lshlrev_b32_e32 v162, 16, v162
	v_lshlrev_b32_e32 v148, 16, v148
	v_lshlrev_b32_e32 v147, 16, v147
	v_lshlrev_b32_e32 v146, 16, v146
	v_lshlrev_b32_e32 v144, 16, v144
	v_lshlrev_b32_e32 v142, 16, v142
	v_lshlrev_b32_e32 v143, 16, v143
	v_lshlrev_b32_e32 v131, 16, v131
	s_branch .LBB0_392
.Lm2u_zero:
	v_mov_b32_e32 v180, 0
	v_mov_b32_e32 v179, 0
	v_mov_b32_e32 v178, 0
	v_mov_b32_e32 v177, 0
	v_mov_b32_e32 v162, 0
	v_mov_b32_e32 v148, 0
	v_mov_b32_e32 v147, 0
	v_mov_b32_e32 v146, 0
	v_mov_b32_e32 v144, 0
	v_mov_b32_e32 v142, 0
	v_mov_b32_e32 v143, 0
	v_mov_b32_e32 v131, 0

.LBB0_589:
	v_add_u32_e32 v49, s9, v71
	ds_read2st64_b32 v[80:81], v49 offset1:1
	v_add_u32_e32 v67, 16, v49
	ds_read2st64_b32 v[82:83], v67 offset0:2 offset1:3
	v_add_u32_e32 v67, 32, v49
	ds_read2st64_b32 v[84:85], v67 offset0:4 offset1:5
	v_add_u32_e32 v67, 48, v49
	ds_read2st64_b32 v[86:87], v67 offset0:6 offset1:7
	v_add_u32_e32 v67, 64, v49
	ds_read2st64_b32 v[88:89], v67 offset0:8 offset1:9
	v_add_u32_e32 v67, 80, v49
	ds_read2st64_b32 v[90:91], v67 offset0:10 offset1:11
	v_add_u32_e32 v67, 96, v49
	ds_read2st64_b32 v[92:93], v67 offset0:12 offset1:13
	v_add_u32_e32 v67, 112, v49
	ds_read2st64_b32 v[94:95], v67 offset0:14 offset1:15
	s_addk_i32 s9, 0x1080
	s_waitcnt lgkmcnt(7)
	v_fma_f32 v80, v42, v44, v80
	v_fma_f32 v81, v43, v45, v81
	v_fma_f32 v80, -v65, v45, v80
	v_fma_f32 v45, v64, v44, v81
	v_mov_b32_e32 v44, v80
	s_waitcnt lgkmcnt(6)
	v_fma_f32 v82, v42, v44, v82
	v_fma_f32 v83, v43, v45, v83
	v_fma_f32 v82, -v65, v45, v82
	v_fma_f32 v45, v64, v44, v83
	v_mov_b32_e32 v44, v82
	s_waitcnt lgkmcnt(5)
	v_fma_f32 v84, v42, v44, v84
	v_fma_f32 v85, v43, v45, v85
	v_fma_f32 v84, -v65, v45, v84
	v_fma_f32 v45, v64, v44, v85
	v_mov_b32_e32 v44, v84
	s_waitcnt lgkmcnt(4)
	v_fma_f32 v86, v42, v44, v86
	v_fma_f32 v87, v43, v45, v87
	v_fma_f32 v86, -v65, v45, v86
	v_fma_f32 v45, v64, v44, v87
	v_mov_b32_e32 v44, v86
	s_waitcnt lgkmcnt(3)
	v_fma_f32 v88, v42, v44, v88
	v_fma_f32 v89, v43, v45, v89
	v_fma_f32 v88, -v65, v45, v88
	v_fma_f32 v45, v64, v44, v89
	v_mov_b32_e32 v44, v88
	s_waitcnt lgkmcnt(2)
	v_fma_f32 v90, v42, v44, v90
	v_fma_f32 v91, v43, v45, v91
	v_fma_f32 v90, -v65, v45, v90
	v_fma_f32 v45, v64, v44, v91
	v_mov_b32_e32 v44, v90
	s_waitcnt lgkmcnt(1)
	v_fma_f32 v92, v42, v44, v92
	v_fma_f32 v93, v43, v45, v93
	v_fma_f32 v92, -v65, v45, v92
	v_fma_f32 v45, v64, v44, v93
	v_mov_b32_e32 v44, v92
	s_waitcnt lgkmcnt(0)
	v_fma_f32 v94, v42, v44, v94
	v_fma_f32 v95, v43, v45, v95
	v_fma_f32 v94, -v65, v45, v94
	v_fma_f32 v45, v64, v44, v95
	v_mov_b32_e32 v44, v94
	s_cmpk_eq_i32 s9, 0x4200
	s_cbranch_scc0 .LBB0_589
	v_mfma_f32_16x16x32_bf16 v[74:77], v[38:41], v[34:37], 0
	s_waitcnt lgkmcnt(0)
	s_mov_b32 s6, 0
	v_mfma_f32_16x16x32_bf16 v[78:81], v[38:41], v[30:33], 0
	s_nop 7
	ds_write2_b32 v70, v74, v78 offset1:16
	ds_write2_b32 v70, v75, v79 offset0:132 offset1:148
	ds_write2_b32 v66, v76, v80 offset0:8 offset1:24
	ds_write2_b32 v66, v77, v81 offset0:140 offset1:156
	v_mfma_f32_16x16x32_bf16 v[74:77], v[38:41], v[22:25], 0
	v_mfma_f32_16x16x32_bf16 v[78:81], v[38:41], v[16:19], 0
	s_nop 7
	ds_write2_b32 v70, v74, v78 offset0:32 offset1:48
	ds_write2_b32 v70, v75, v79 offset0:164 offset1:180
	ds_write2_b32 v66, v76, v80 offset0:40 offset1:56
	ds_write2_b32 v66, v77, v81 offset0:172 offset1:188
	v_mfma_f32_16x16x32_bf16 v[74:77], v[38:41], v[12:15], 0
	v_mfma_f32_16x16x32_bf16 v[78:81], v[38:41], v[8:11], 0
	s_nop 7
	ds_write2_b32 v70, v74, v78 offset0:64 offset1:80
	ds_write2_b32 v70, v75, v79 offset0:196 offset1:212
	ds_write2_b32 v66, v76, v80 offset0:72 offset1:88
	ds_write2_b32 v66, v77, v81 offset0:204 offset1:220
	v_mfma_f32_16x16x32_bf16 v[74:77], v[38:41], v[4:7], 0
	v_mfma_f32_16x16x32_bf16 v[38:41], v[38:41], v[0:3], 0
	s_nop 7
	ds_write2_b32 v70, v74, v38 offset0:96 offset1:112
	ds_write2_b32 v70, v75, v39 offset0:228 offset1:244
	ds_write2_b32 v66, v76, v40 offset0:104 offset1:120
	ds_write2_b32 v66, v77, v41 offset0:236 offset1:252
	v_mfma_f32_16x16x32_bf16 v[34:37], v[26:29], v[34:37], 0
	v_mfma_f32_16x16x32_bf16 v[30:33], v[26:29], v[30:33], 0
	s_nop 7
	ds_write2_b32 v46, v34, v30 offset0:64 offset1:80
	ds_write2_b32 v46, v35, v31 offset0:196 offset1:212
	ds_write2_b32 v47, v36, v32 offset0:72 offset1:88
	ds_write2_b32 v47, v37, v33 offset0:204 offset1:220
	v_mfma_f32_16x16x32_bf16 v[22:25], v[26:29], v[22:25], 0
	v_mfma_f32_16x16x32_bf16 v[16:19], v[26:29], v[16:19], 0
	s_nop 7
	ds_write2_b32 v46, v22, v16 offset0:96 offset1:112
	ds_write2_b32 v46, v23, v17 offset0:228 offset1:244
	ds_write2_b32 v47, v24, v18 offset0:104 offset1:120
	ds_write2_b32 v47, v25, v19 offset0:236 offset1:252
	v_mfma_f32_16x16x32_bf16 v[12:15], v[26:29], v[12:15], 0
	v_mfma_f32_16x16x32_bf16 v[8:11], v[26:29], v[8:11], 0
	s_nop 7
	ds_write2_b32 v46, v12, v8 offset0:128 offset1:144
	ds_write2_b32 v47, v13, v9 offset0:4 offset1:20
	ds_write2_b32 v47, v14, v10 offset0:136 offset1:152
	ds_write2_b32 v48, v15, v11 offset0:12 offset1:28
	v_mfma_f32_16x16x32_bf16 v[4:7], v[26:29], v[4:7], 0
	v_mfma_f32_16x16x32_bf16 v[0:3], v[26:29], v[0:3], 0
	s_nop 7
	ds_write2_b32 v46, v4, v0 offset0:160 offset1:176
	ds_write2_b32 v47, v5, v1 offset0:36 offset1:52
	ds_write2_b32 v47, v6, v2 offset0:168 offset1:184
	ds_write2_b32 v48, v7, v3 offset0:44 offset1:60
	s_waitcnt lgkmcnt(0)
.LBB0_591:
	v_add_u32_e32 v49, s6, v71
	ds_read2st64_b32 v[80:81], v49 offset1:1
	v_add_u32_e32 v67, 16, v49
	ds_read2st64_b32 v[82:83], v67 offset0:2 offset1:3
	v_add_u32_e32 v67, 32, v49
	ds_read2st64_b32 v[84:85], v67 offset0:4 offset1:5
	v_add_u32_e32 v67, 48, v49
	ds_read2st64_b32 v[86:87], v67 offset0:6 offset1:7
	v_add_u32_e32 v67, 64, v49
	ds_read2st64_b32 v[88:89], v67 offset0:8 offset1:9
	v_add_u32_e32 v67, 80, v49
	ds_read2st64_b32 v[90:91], v67 offset0:10 offset1:11
	v_add_u32_e32 v67, 96, v49
	ds_read2st64_b32 v[92:93], v67 offset0:12 offset1:13
	v_add_u32_e32 v67, 112, v49
	ds_read2st64_b32 v[94:95], v67 offset0:14 offset1:15
	s_addk_i32 s6, 0x1080
	s_waitcnt lgkmcnt(7)
	v_fma_f32 v80, v42, v44, v80
	v_fma_f32 v81, v43, v45, v81
	v_fma_f32 v80, -v65, v45, v80
	v_fma_f32 v45, v64, v44, v81
	v_mov_b32_e32 v44, v80
	s_waitcnt lgkmcnt(6)
	v_fma_f32 v82, v42, v44, v82
	v_fma_f32 v83, v43, v45, v83
	v_fma_f32 v82, -v65, v45, v82
	v_fma_f32 v45, v64, v44, v83
	v_mov_b32_e32 v44, v82
	s_waitcnt lgkmcnt(5)
	v_fma_f32 v84, v42, v44, v84
	v_fma_f32 v85, v43, v45, v85
	v_fma_f32 v84, -v65, v45, v84
	v_fma_f32 v45, v64, v44, v85
	v_mov_b32_e32 v44, v84
	s_waitcnt lgkmcnt(4)
	v_fma_f32 v86, v42, v44, v86
	v_fma_f32 v87, v43, v45, v87
	v_fma_f32 v86, -v65, v45, v86
	v_fma_f32 v45, v64, v44, v87
	v_mov_b32_e32 v44, v86
	s_waitcnt lgkmcnt(3)
	v_fma_f32 v88, v42, v44, v88
	v_fma_f32 v89, v43, v45, v89
	v_fma_f32 v88, -v65, v45, v88
	v_fma_f32 v45, v64, v44, v89
	v_mov_b32_e32 v44, v88
	s_waitcnt lgkmcnt(2)
	v_fma_f32 v90, v42, v44, v90
	v_fma_f32 v91, v43, v45, v91
	v_fma_f32 v90, -v65, v45, v90
	v_fma_f32 v45, v64, v44, v91
	v_mov_b32_e32 v44, v90
	s_waitcnt lgkmcnt(1)
	v_fma_f32 v92, v42, v44, v92
	v_fma_f32 v93, v43, v45, v93
	v_fma_f32 v92, -v65, v45, v92
	v_fma_f32 v45, v64, v44, v93
	v_mov_b32_e32 v44, v92
	s_waitcnt lgkmcnt(0)
	v_fma_f32 v94, v42, v44, v94
	v_fma_f32 v95, v43, v45, v95
	v_fma_f32 v94, -v65, v45, v94
	v_fma_f32 v45, v64, v44, v95
	v_mov_b32_e32 v44, v94
	s_cmpk_lg_i32 s6, 0x4200
	s_cbranch_scc1 .LBB0_591
	v_add_u32_e32 v0, s8, v72
	s_waitcnt lgkmcnt(0)
	v_ashrrev_i32_e32 v1, 31, v0
	v_lshlrev_b64 v[0:1], 9, v[0:1]
	v_lshl_add_u64 v[0:1], v[54:55], 0, v[0:1]
	s_mov_b32 s9, 1
	s_mov_b64 s[6:7], 0
	s_and_b64 vcc, exec, s[4:5]
	global_store_dwordx2 v[0:1], v[44:45], off
	s_cbranch_vccz .LBB0_580
	s_barrier
	s_branch .LBB0_571

.LBB0_2090:
	s_and_b32 s4, s8, 0xffffffe0
	s_and_b32 s11, s10, 15
	v_add_u32_e32 v250, s4, v8
	v_ashrrev_i32_e32 v251, 31, v250
	v_lshlrev_b64 v[250:251], 11, v[250:251]
	v_lshl_add_u64 v[250:251], s[2:3], 0, v[250:251]
	s_lshl_b32 s24, s11, 7
	v_lshl_add_u64 v[250:251], v[250:251], 0, s[24:25]
	v_mov_b32_e32 v252, v4
	v_mov_b32_e32 v253, v20
	v_lshl_add_u64 v[250:251], v[250:251], 0, v[252:253]
	global_load_dwordx2 v[252:253], v[250:251], off
	v_or_b32_e32 v5, s4, v21
	v_mad_i64_i32 v[6:7], s[12:13], v5, s91, v[0:1]
	v_lshl_or_b32 v5, s11, 6, v21
	v_mul_u32_u24_e32 v5, 0xb00, v5
	v_lshlrev_b32_e32 v16, 1, v5
	v_mov_b32_e32 v17, v20
	v_add_co_u32_e32 v148, vcc, 0x16000, v6
	v_lshl_add_u64 v[146:147], v[2:3], 0, v[16:17]
	s_nop 0
	v_addc_co_u32_e32 v149, vcc, 0, v7, vcc
	v_add_co_u32_e32 v156, vcc, 0x16000, v146
	s_nop 1
	v_addc_co_u32_e32 v157, vcc, 0, v147, vcc
	v_add_co_u32_e32 v162, vcc, 0x2c000, v146
	s_nop 1
	v_addc_co_u32_e32 v163, vcc, 0, v147, vcc
	v_add_co_u32_e32 v164, vcc, 0x42000, v146
	s_nop 1
	v_addc_co_u32_e32 v165, vcc, 0, v147, vcc
	global_load_dwordx4 v[50:53], v[6:7], off
	global_load_dwordx4 v[54:57], v[148:149], off
	global_load_dwordx4 v[58:61], v[146:147], off
	global_load_dwordx4 v[62:65], v[156:157], off
	global_load_dwordx4 v[66:69], v[162:163], off
	global_load_dwordx4 v[70:73], v[164:165], off
	global_load_dwordx4 v[74:77], v[6:7], off offset:64
	global_load_dwordx4 v[78:81], v[148:149], off offset:64
	global_load_dwordx4 v[82:85], v[146:147], off offset:64
	global_load_dwordx4 v[86:89], v[156:157], off offset:64
	global_load_dwordx4 v[90:93], v[162:163], off offset:64
	global_load_dwordx4 v[94:97], v[164:165], off offset:64
	global_load_dwordx4 v[98:101], v[6:7], off offset:128
	global_load_dwordx4 v[102:105], v[148:149], off offset:128
	global_load_dwordx4 v[106:109], v[146:147], off offset:128
	global_load_dwordx4 v[110:113], v[156:157], off offset:128
	global_load_dwordx4 v[114:117], v[162:163], off offset:128
	global_load_dwordx4 v[118:121], v[164:165], off offset:128
	global_load_dwordx4 v[122:125], v[6:7], off offset:192
	global_load_dwordx4 v[126:129], v[148:149], off offset:192
	global_load_dwordx4 v[130:133], v[146:147], off offset:192
	global_load_dwordx4 v[134:137], v[156:157], off offset:192
	global_load_dwordx4 v[138:141], v[162:163], off offset:192
	global_load_dwordx4 v[142:145], v[164:165], off offset:192
	global_load_dwordx4 v[166:169], v[6:7], off offset:256
	global_load_dwordx4 v[170:173], v[148:149], off offset:256
	global_load_dwordx4 v[174:177], v[146:147], off offset:256
	global_load_dwordx4 v[178:181], v[156:157], off offset:256
	global_load_dwordx4 v[182:185], v[162:163], off offset:256
	global_load_dwordx4 v[186:189], v[164:165], off offset:256
	global_load_dwordx4 v[208:211], v[6:7], off offset:320
	global_load_dwordx4 v[212:215], v[148:149], off offset:320
	global_load_dwordx4 v[216:219], v[146:147], off offset:320
	global_load_dwordx4 v[220:223], v[156:157], off offset:320
	global_load_dwordx4 v[224:227], v[162:163], off offset:320
	global_load_dwordx4 v[228:231], v[164:165], off offset:320
	s_waitcnt vmcnt(30)
	v_mfma_f32_16x16x32_bf16 v[30:33], v[58:61], v[50:53], 0
	v_mfma_f32_16x16x32_bf16 v[42:45], v[62:65], v[50:53], 0
	v_mfma_f32_16x16x32_bf16 v[46:49], v[66:69], v[50:53], 0
	v_mfma_f32_16x16x32_bf16 v[16:19], v[70:73], v[50:53], 0
	v_mfma_f32_16x16x32_bf16 v[22:25], v[58:61], v[54:57], 0
	v_mfma_f32_16x16x32_bf16 v[34:37], v[62:65], v[54:57], 0
	v_mfma_f32_16x16x32_bf16 v[38:41], v[66:69], v[54:57], 0
	v_mfma_f32_16x16x32_bf16 v[26:29], v[70:73], v[54:57], 0
	global_load_dwordx4 v[50:53], v[6:7], off offset:384
	global_load_dwordx4 v[54:57], v[148:149], off offset:384
	global_load_dwordx4 v[58:61], v[146:147], off offset:384
	global_load_dwordx4 v[62:65], v[156:157], off offset:384
	global_load_dwordx4 v[66:69], v[162:163], off offset:384
	global_load_dwordx4 v[70:73], v[164:165], off offset:384
	s_waitcnt vmcnt(30)
	v_mfma_f32_16x16x32_bf16 v[30:33], v[82:85], v[74:77], v[30:33]
	v_mfma_f32_16x16x32_bf16 v[42:45], v[86:89], v[74:77], v[42:45]
	v_mfma_f32_16x16x32_bf16 v[46:49], v[90:93], v[74:77], v[46:49]
	v_mfma_f32_16x16x32_bf16 v[16:19], v[94:97], v[74:77], v[16:19]
	v_mfma_f32_16x16x32_bf16 v[22:25], v[82:85], v[78:81], v[22:25]
	v_mfma_f32_16x16x32_bf16 v[34:37], v[86:89], v[78:81], v[34:37]
	v_mfma_f32_16x16x32_bf16 v[38:41], v[90:93], v[78:81], v[38:41]
	v_mfma_f32_16x16x32_bf16 v[26:29], v[94:97], v[78:81], v[26:29]
	global_load_dwordx4 v[74:77], v[6:7], off offset:448
	global_load_dwordx4 v[78:81], v[148:149], off offset:448
	global_load_dwordx4 v[82:85], v[146:147], off offset:448
	global_load_dwordx4 v[86:89], v[156:157], off offset:448
	global_load_dwordx4 v[90:93], v[162:163], off offset:448
	global_load_dwordx4 v[94:97], v[164:165], off offset:448
	s_waitcnt vmcnt(30)
	v_mfma_f32_16x16x32_bf16 v[30:33], v[106:109], v[98:101], v[30:33]
	v_mfma_f32_16x16x32_bf16 v[42:45], v[110:113], v[98:101], v[42:45]
	v_mfma_f32_16x16x32_bf16 v[46:49], v[114:117], v[98:101], v[46:49]
	v_mfma_f32_16x16x32_bf16 v[16:19], v[118:121], v[98:101], v[16:19]
	v_mfma_f32_16x16x32_bf16 v[22:25], v[106:109], v[102:105], v[22:25]
	v_mfma_f32_16x16x32_bf16 v[34:37], v[110:113], v[102:105], v[34:37]
	v_mfma_f32_16x16x32_bf16 v[38:41], v[114:117], v[102:105], v[38:41]
	v_mfma_f32_16x16x32_bf16 v[26:29], v[118:121], v[102:105], v[26:29]
	global_load_dwordx4 v[98:101], v[6:7], off offset:512
	global_load_dwordx4 v[102:105], v[148:149], off offset:512
	global_load_dwordx4 v[106:109], v[146:147], off offset:512
	global_load_dwordx4 v[110:113], v[156:157], off offset:512
	global_load_dwordx4 v[114:117], v[162:163], off offset:512
	global_load_dwordx4 v[118:121], v[164:165], off offset:512
	s_waitcnt vmcnt(30)
	v_mfma_f32_16x16x32_bf16 v[30:33], v[130:133], v[122:125], v[30:33]
	v_mfma_f32_16x16x32_bf16 v[42:45], v[134:137], v[122:125], v[42:45]
	v_mfma_f32_16x16x32_bf16 v[46:49], v[138:141], v[122:125], v[46:49]
	v_mfma_f32_16x16x32_bf16 v[16:19], v[142:145], v[122:125], v[16:19]
	v_mfma_f32_16x16x32_bf16 v[22:25], v[130:133], v[126:129], v[22:25]
	v_mfma_f32_16x16x32_bf16 v[34:37], v[134:137], v[126:129], v[34:37]
	v_mfma_f32_16x16x32_bf16 v[38:41], v[138:141], v[126:129], v[38:41]
	v_mfma_f32_16x16x32_bf16 v[26:29], v[142:145], v[126:129], v[26:29]
	global_load_dwordx4 v[122:125], v[6:7], off offset:576
	global_load_dwordx4 v[126:129], v[148:149], off offset:576
	global_load_dwordx4 v[130:133], v[146:147], off offset:576
	global_load_dwordx4 v[134:137], v[156:157], off offset:576
	global_load_dwordx4 v[138:141], v[162:163], off offset:576
	global_load_dwordx4 v[142:145], v[164:165], off offset:576
	s_waitcnt vmcnt(30)
	v_mfma_f32_16x16x32_bf16 v[30:33], v[174:177], v[166:169], v[30:33]
	v_mfma_f32_16x16x32_bf16 v[42:45], v[178:181], v[166:169], v[42:45]
	v_mfma_f32_16x16x32_bf16 v[46:49], v[182:185], v[166:169], v[46:49]
	v_mfma_f32_16x16x32_bf16 v[16:19], v[186:189], v[166:169], v[16:19]
	v_mfma_f32_16x16x32_bf16 v[22:25], v[174:177], v[170:173], v[22:25]
	v_mfma_f32_16x16x32_bf16 v[34:37], v[178:181], v[170:173], v[34:37]
	v_mfma_f32_16x16x32_bf16 v[38:41], v[182:185], v[170:173], v[38:41]
	v_mfma_f32_16x16x32_bf16 v[26:29], v[186:189], v[170:173], v[26:29]
	global_load_dwordx4 v[166:169], v[6:7], off offset:640
	global_load_dwordx4 v[170:173], v[148:149], off offset:640
	global_load_dwordx4 v[174:177], v[146:147], off offset:640
	global_load_dwordx4 v[178:181], v[156:157], off offset:640
	global_load_dwordx4 v[182:185], v[162:163], off offset:640
	global_load_dwordx4 v[186:189], v[164:165], off offset:640
	s_waitcnt vmcnt(30)
	v_mfma_f32_16x16x32_bf16 v[30:33], v[216:219], v[208:211], v[30:33]
	v_mfma_f32_16x16x32_bf16 v[42:45], v[220:223], v[208:211], v[42:45]
	v_mfma_f32_16x16x32_bf16 v[46:49], v[224:227], v[208:211], v[46:49]
	v_mfma_f32_16x16x32_bf16 v[16:19], v[228:231], v[208:211], v[16:19]
	v_mfma_f32_16x16x32_bf16 v[22:25], v[216:219], v[212:215], v[22:25]
	v_mfma_f32_16x16x32_bf16 v[34:37], v[220:223], v[212:215], v[34:37]
	v_mfma_f32_16x16x32_bf16 v[38:41], v[224:227], v[212:215], v[38:41]
	v_mfma_f32_16x16x32_bf16 v[26:29], v[228:231], v[212:215], v[26:29]
	s_waitcnt vmcnt(24)
	v_mfma_f32_16x16x32_bf16 v[30:33], v[58:61], v[50:53], v[30:33]
	v_mfma_f32_16x16x32_bf16 v[42:45], v[62:65], v[50:53], v[42:45]
	v_mfma_f32_16x16x32_bf16 v[46:49], v[66:69], v[50:53], v[46:49]
	v_mfma_f32_16x16x32_bf16 v[16:19], v[70:73], v[50:53], v[16:19]
	v_mfma_f32_16x16x32_bf16 v[22:25], v[58:61], v[54:57], v[22:25]
	v_mfma_f32_16x16x32_bf16 v[34:37], v[62:65], v[54:57], v[34:37]
	v_mfma_f32_16x16x32_bf16 v[38:41], v[66:69], v[54:57], v[38:41]
	v_mfma_f32_16x16x32_bf16 v[26:29], v[70:73], v[54:57], v[26:29]
	s_waitcnt vmcnt(18)
	v_mfma_f32_16x16x32_bf16 v[30:33], v[82:85], v[74:77], v[30:33]
	v_mfma_f32_16x16x32_bf16 v[42:45], v[86:89], v[74:77], v[42:45]
	v_mfma_f32_16x16x32_bf16 v[46:49], v[90:93], v[74:77], v[46:49]
	v_mfma_f32_16x16x32_bf16 v[16:19], v[94:97], v[74:77], v[16:19]
	v_mfma_f32_16x16x32_bf16 v[22:25], v[82:85], v[78:81], v[22:25]
	v_mfma_f32_16x16x32_bf16 v[34:37], v[86:89], v[78:81], v[34:37]
	v_mfma_f32_16x16x32_bf16 v[38:41], v[90:93], v[78:81], v[38:41]
	v_mfma_f32_16x16x32_bf16 v[26:29], v[94:97], v[78:81], v[26:29]
	s_waitcnt vmcnt(12)
	v_mfma_f32_16x16x32_bf16 v[30:33], v[106:109], v[98:101], v[30:33]
	v_mfma_f32_16x16x32_bf16 v[42:45], v[110:113], v[98:101], v[42:45]
	v_mfma_f32_16x16x32_bf16 v[46:49], v[114:117], v[98:101], v[46:49]
	v_mfma_f32_16x16x32_bf16 v[16:19], v[118:121], v[98:101], v[16:19]
	v_mfma_f32_16x16x32_bf16 v[22:25], v[106:109], v[102:105], v[22:25]
	v_mfma_f32_16x16x32_bf16 v[34:37], v[110:113], v[102:105], v[34:37]
	v_mfma_f32_16x16x32_bf16 v[38:41], v[114:117], v[102:105], v[38:41]
	v_mfma_f32_16x16x32_bf16 v[26:29], v[118:121], v[102:105], v[26:29]
	s_waitcnt vmcnt(6)
	v_mfma_f32_16x16x32_bf16 v[30:33], v[130:133], v[122:125], v[30:33]
	v_mfma_f32_16x16x32_bf16 v[42:45], v[134:137], v[122:125], v[42:45]
	v_mfma_f32_16x16x32_bf16 v[46:49], v[138:141], v[122:125], v[46:49]
	v_mfma_f32_16x16x32_bf16 v[16:19], v[142:145], v[122:125], v[16:19]
	v_mfma_f32_16x16x32_bf16 v[22:25], v[130:133], v[126:129], v[22:25]
	v_mfma_f32_16x16x32_bf16 v[34:37], v[134:137], v[126:129], v[34:37]
	v_mfma_f32_16x16x32_bf16 v[38:41], v[138:141], v[126:129], v[38:41]
	v_mfma_f32_16x16x32_bf16 v[26:29], v[142:145], v[126:129], v[26:29]
	s_waitcnt vmcnt(0)
	v_mfma_f32_16x16x32_bf16 v[30:33], v[174:177], v[166:169], v[30:33]
	v_mfma_f32_16x16x32_bf16 v[42:45], v[178:181], v[166:169], v[42:45]
	v_mfma_f32_16x16x32_bf16 v[46:49], v[182:185], v[166:169], v[46:49]
	v_mfma_f32_16x16x32_bf16 v[16:19], v[186:189], v[166:169], v[16:19]
	v_mfma_f32_16x16x32_bf16 v[22:25], v[174:177], v[170:173], v[22:25]
	v_mfma_f32_16x16x32_bf16 v[34:37], v[178:181], v[170:173], v[34:37]
	v_mfma_f32_16x16x32_bf16 v[38:41], v[182:185], v[170:173], v[38:41]
	v_mfma_f32_16x16x32_bf16 v[26:29], v[186:189], v[170:173], v[26:29]
	s_nop 7
	ds_write_b128 v14, v[30:33]
	ds_write_b128 v14, v[42:45] offset:64
	ds_write_b128 v14, v[46:49] offset:128
	s_nop 0
	ds_write_b128 v14, v[16:19] offset:192
	ds_write_b128 v14, v[22:25] offset:4096
	ds_write_b128 v14, v[34:37] offset:4160
	ds_write_b128 v14, v[38:41] offset:4224
	ds_write_b128 v14, v[26:29] offset:4288
	s_waitcnt lgkmcnt(0)
	s_barrier
	ds_read_b128 v[16:19], v9
	ds_read_b128 v[22:25], v9 offset:8192
	s_lshl_b32 s24, s11, 7
	v_mov_b32_e32 v5, v20
	s_waitcnt lgkmcnt(0)
	v_pk_add_f32 v[6:7], v[18:19], v[24:25]
	v_pk_add_f32 v[22:23], v[16:17], v[22:23]
	ds_read_b128 v[16:19], v9 offset:16384
	s_waitcnt lgkmcnt(0)
	v_pk_add_f32 v[6:7], v[6:7], v[18:19]
	v_pk_add_f32 v[22:23], v[22:23], v[16:17]
	ds_read_b128 v[16:19], v9 offset:24576
	s_waitcnt lgkmcnt(0)
	v_pk_add_f32 v[6:7], v[6:7], v[18:19]
	v_pk_add_f32 v[22:23], v[22:23], v[16:17]
	ds_read_b128 v[16:19], v9 offset:32768
	s_waitcnt lgkmcnt(0)
	v_pk_add_f32 v[6:7], v[6:7], v[18:19]
	v_pk_add_f32 v[22:23], v[22:23], v[16:17]
	ds_read_b128 v[16:19], v9 offset:40960
	s_waitcnt lgkmcnt(0)
	v_pk_add_f32 v[6:7], v[6:7], v[18:19]
	v_pk_add_f32 v[22:23], v[22:23], v[16:17]
	ds_read_b128 v[16:19], v9 offset:49152
	s_waitcnt lgkmcnt(0)
	v_pk_add_f32 v[6:7], v[6:7], v[18:19]
	v_pk_add_f32 v[22:23], v[22:23], v[16:17]
	ds_read_b128 v[16:19], v9 offset:57344
	s_waitcnt lgkmcnt(0)
	v_pk_add_f32 v[18:19], v[6:7], v[18:19]
	v_add_u32_e32 v6, s4, v8
	v_ashrrev_i32_e32 v7, 31, v6
	v_pk_add_f32 v[16:17], v[22:23], v[16:17]
	v_lshlrev_b64 v[22:23], 11, v[6:7]
	v_lshl_add_u64 v[22:23], s[2:3], 0, v[22:23]
	v_lshl_add_u64 v[22:23], v[22:23], 0, s[24:25]
	v_lshl_add_u64 v[22:23], v[22:23], 0, v[4:5]
	v_mov_b32_e32 v24, v252
	v_mov_b32_e32 v25, v253
	s_waitcnt vmcnt(0)
	v_lshlrev_b32_e32 v26, 16, v24
	v_and_b32_e32 v27, 0xffff0000, v24
	v_lshlrev_b32_e32 v24, 16, v25
	v_and_b32_e32 v25, 0xffff0000, v25
	v_pk_fma_f32 v[18:19], v[18:19], 0.5, v[24:25] op_sel_hi:[1,0,1]
	v_pk_fma_f32 v[16:17], v[16:17], 0.5, v[26:27] op_sel_hi:[1,0,1]
	v_mul_f32_e32 v15, v19, v19
	v_mul_f32_e32 v5, v17, v17
	v_fmac_f32_e32 v5, v16, v16
	v_fmac_f32_e32 v15, v18, v18
	v_add_f32_e32 v5, v5, v15
	ds_bpermute_b32 v15, v10, v5
	v_cvt_pk_bf16_f32 v24, v16, v17
	v_cvt_pk_bf16_f32 v25, v18, v19
	global_store_dwordx2 v[22:23], v[24:25], off
	s_waitcnt lgkmcnt(0)
	v_add_f32_e32 v5, v5, v15
	ds_bpermute_b32 v15, v11, v5
	s_waitcnt lgkmcnt(0)
	v_add_f32_e32 v5, v5, v15
	ds_bpermute_b32 v15, v12, v5
	s_waitcnt lgkmcnt(0)
	v_add_f32_e32 v5, v5, v15
	ds_bpermute_b32 v15, v13, v5
	s_and_saveexec_b64 s[4:5], s[38:39]
	s_cbranch_execz .LBB0_2089
	v_lshlrev_b64 v[6:7], 6, v[6:7]
	v_lshl_add_u64 v[6:7], s[6:7], 0, v[6:7]
	s_lshl_b32 s24, s11, 2
	s_waitcnt lgkmcnt(0)
	v_add_f32_e32 v5, v5, v15
	v_lshl_add_u64 v[6:7], v[6:7], 0, s[24:25]
	global_store_dword v[6:7], v5, off
	s_branch .LBB0_2089
